# half of the w_in f32->bf16 transposition (column tiles first used by z rounds 2-3) moved out of P0 into the 32 workgroups that have no z units in P1; z workgroups check a completion counter before rou
# speedup vs baseline: 1.0208x; 1.0139x over previous
; #define LAS __attribute__((address_space(3)))
; __device__ __forceinline__ void p0_transpose_item(const float* W, int K, int N, bf16_t* WT, const float* kscale, LAS float* scr, int item, int lane) {
;     const int nblk = N / 32, kb = item / nblk, nb = item % nblk, k0 = 64 * kb, n0 = 32 * nb;
;     const int n4 = (lane & 7) * 4, kr = lane >> 3;
;     f32x4 v[8];
; #pragma unroll
; __global__ void __launch_bounds__(NWAVES * 64, 2) fwd(Args args) {
;     ...
;         for (int it = gw; it < NITEMS; it += NGW) {
;             int r = it;
;             if (r < I_IN) { p0_transpose_item(w_in, DM, DIN, WinT, nullptr, scr, r, lane); continue; } r -= I_IN;
;             p0_transpose_item(w_proj, PLE, DM, WpT, nullptr, scr, r, lane);
;         }
.LBB0_8:
	s_add_u32 s26, s80, 0x100000
	s_addc_u32 s27, s81, 0
	s_add_u32 s28, s80, 0x200000
	s_addc_u32 s29, s81, 0
	s_add_u32 s24, s80, 0x2e00000
	s_addc_u32 s25, s81, 0
	s_lshr_b32 s60, s92, 6
	s_load_dwordx8 s[8:15], s[0:1], 0x60
	s_cmp_lt_i32 s82, 1
	s_cselect_b64 s[2:3], -1, 0
	s_cmp_gt_i32 s83, 0
	s_cselect_b64 s[4:5], -1, 0
	s_lshl_b32 s6, s60, 14
	s_and_b64 s[4:5], s[2:3], s[4:5]
	s_add_i32 s61, s6, 0
	s_andn2_b64 vcc, exec, s[4:5]
	s_cbranch_vccnz .LBB0_40
	s_load_dwordx8 s[16:23], s[0:1], 0x0
	s_lshl_b32 s4, s95, 3
	v_mbcnt_lo_u32_b32 v0, -1, 0
	s_add_i32 s4, s4, s60
	s_lshl_b32 s6, s78, 3
	v_mbcnt_hi_u32_b32 v8, -1, v0
	s_cmpk_gt_i32 s4, 0xeff
	s_mov_b32 s31, 0
	v_mov_b32_e32 v16, v8
	s_cbranch_scc1 .LBB0_16
	v_and_b32_e32 v2, 7, v16
	v_ashrrev_i32_e32 v9, 3, v16
	v_lshlrev_b32_e32 v6, 4, v2
	s_movk_i32 s5, 0x84
	v_add_u32_e32 v14, s61, v6
	v_mul_lo_u32 v15, v9, s5
	v_mov_b32_e32 v7, 0
	v_mul_u32_u24_e32 v4, 0x420, v2
	v_lshlrev_b32_e32 v5, 2, v9
	v_add_u32_e32 v14, v14, v15
	s_waitcnt lgkmcnt(0)
	v_lshl_add_u64 v[0:1], s[14:15], 0, v[6:7]
	v_add_u32_e32 v10, 8, v9
	v_add_u32_e32 v11, 16, v9
	v_add_u32_e32 v12, 24, v9
	v_lshl_add_u64 v[2:3], s[24:25], 0, v[6:7]
	v_add3_u32 v13, s61, v4, v5
	v_lshl_add_u64 v[4:5], s[22:23], 0, v[6:7]
	v_lshl_add_u64 v[6:7], s[28:29], 0, v[6:7]
	s_lshl_b32 s5, s4, 5
	s_lshl_b32 s7, s6, 5
	v_add_u32_e32 v15, 0x420, v14
	v_add_u32_e32 v17, 0x428, v14
	v_add_u32_e32 v18, 0x840, v14
	v_add_u32_e32 v19, 0x848, v14
	v_add_u32_e32 v20, 0xc60, v14
	v_add_u32_e32 v21, 0xc68, v14
	v_add_u32_e32 v22, 0x1080, v14
	v_add_u32_e32 v23, 0x1088, v14
	v_add_u32_e32 v24, 0x14a0, v14
	v_add_u32_e32 v25, 0x14a8, v14
	v_add_u32_e32 v26, 0x18c0, v14
	v_add_u32_e32 v27, 0x18c8, v14
	v_add_u32_e32 v28, 0x1ce0, v14
	v_add_u32_e32 v29, 0x1ce8, v14
	s_movk_i32 s22, 0x7000
	s_mov_b32 s23, s4
	s_branch .LBB0_12
.LBB0_11:
	s_add_i32 s23, s23, s6
	s_add_i32 s5, s5, s7
	s_cmpk_gt_i32 s23, 0xeff
	s_cbranch_scc1 .LBB0_16
.LBB0_12:
	s_cmpk_gt_i32 s23, 0xdff
	s_mov_b64 s[14:15], -1
	s_cbranch_scc1 .LBB0_14
	s_andn2_b64 vcc, exec, s[14:15]
	s_cbranch_vccnz .LBB0_11
	s_branch .LBB0_15

; #define LAS __attribute__((address_space(3)))
; __device__ __forceinline__ unsigned cvtpk(float lo, float hi) { f32x2 v = {lo, hi}; bf16x2_t b = __builtin_convertvector(v, bf16x2_t); return __builtin_bit_cast(unsigned, b); }
; __device__ __forceinline__ void p0_transpose_item(const float* W, int K, int N, bf16_t* WT, const float* kscale, LAS float* scr, int item, int lane) {
;     const int nblk = N / 32, kb = item / nblk, nb = item % nblk, k0 = 64 * kb, n0 = 32 * nb;
;     const int n4 = (lane & 7) * 4, kr = lane >> 3;
;     f32x4 v[8];
; #pragma unroll
;     for (int i = 0; i < 8; ++i) v[i] = __builtin_nontemporal_load((const f32x4*)(W + (size_t)(k0 + kr + 8 * i) * N + n0 + n4));
; #pragma unroll
;     for (int i = 0; i < 8; ++i) { const int kk = kr + 8 * i; const float sc = kscale ? kscale[k0 + kk] : 1.0f; LAS float* d = scr + kk * 33 + n4;
;         d[0] = v[i].x * sc; d[1] = v[i].y * sc; d[2] = v[i].z * sc; d[3] = v[i].w * sc; }
;     asm volatile("s_waitcnt lgkmcnt(0)" ::: "memory");
;     const int c = lane & 7;
; #pragma unroll
;     for (int j = 0; j < 4; ++j) { const int n = (lane >> 3) + 8 * j; const LAS float* sp = scr + (8 * c) * 33 + n;
;         u32x4 o; o.x = cvtpk(sp[0 * 33], sp[1 * 33]); o.y = cvtpk(sp[2 * 33], sp[3 * 33]); o.z = cvtpk(sp[4 * 33], sp[5 * 33]); o.w = cvtpk(sp[6 * 33], sp[7 * 33]);
;         *(u32x4*)(WT + (size_t)(n0 + n) * K + k0 + 8 * c) = o; }
;     asm volatile("s_waitcnt lgkmcnt(0)" ::: "memory");
; }
.LBB0_15:
	s_mul_i32 s15, s23, 0x925
	s_lshr_b32 s15, s15, 18
	s_mul_i32 s34, s15, 0x70
	s_sub_i32 s34, s23, s34
	s_cmp_ge_u32 s34, 56
	s_cselect_b32 s14, 56, 0
	s_add_i32 s34, s34, s14
	s_lshl_b32 s34, s34, 5
	s_lshl_b32 s14, s15, 6
	s_ashr_i32 s35, s34, 31
	v_add_u32_e32 v60, s14, v9
	v_lshl_add_u64 v[58:59], s[34:35], 2, v[4:5]
	v_mad_i64_i32 v[38:39], s[36:37], v60, s22, v[58:59]
	v_add_u32_e32 v30, 8, v60
	v_mad_i64_i32 v[40:41], s[36:37], v30, s22, v[58:59]
	global_load_dwordx4 v[30:33], v[38:39], off nt
	global_load_dwordx4 v[34:37], v[40:41], off nt
	v_add_u32_e32 v38, 16, v60
	v_mad_i64_i32 v[46:47], s[36:37], v38, s22, v[58:59]
	v_add_u32_e32 v38, 24, v60
	v_mad_i64_i32 v[48:49], s[36:37], v38, s22, v[58:59]
	global_load_dwordx4 v[38:41], v[46:47], off nt
	global_load_dwordx4 v[42:45], v[48:49], off nt
	v_add_u32_e32 v46, 32, v60
	v_mad_i64_i32 v[54:55], s[36:37], v46, s22, v[58:59]
	v_add_u32_e32 v46, 40, v60
	v_mad_i64_i32 v[56:57], s[36:37], v46, s22, v[58:59]
	global_load_dwordx4 v[46:49], v[54:55], off nt
	global_load_dwordx4 v[50:53], v[56:57], off nt
	v_add_u32_e32 v54, 48, v60
	v_mad_i64_i32 v[54:55], s[36:37], v54, s22, v[58:59]
	global_load_dwordx4 v[54:57], v[54:55], off nt
	v_add_u32_e32 v60, 56, v60
	v_mad_i64_i32 v[58:59], s[36:37], v60, s22, v[58:59]
	global_load_dwordx4 v[58:61], v[58:59], off nt
	v_add_u32_e32 v64, s34, v9
	s_ashr_i32 s15, s14, 31
	v_ashrrev_i32_e32 v65, 31, v64
	v_add_u32_e32 v66, 8, v64
	v_lshl_add_u64 v[62:63], s[14:15], 1, v[6:7]
	v_lshlrev_b64 v[68:69], 12, v[64:65]
	v_ashrrev_i32_e32 v67, 31, v66
	v_lshl_add_u64 v[68:69], v[62:63], 0, v[68:69]
	v_lshlrev_b64 v[66:67], 12, v[66:67]
	v_lshl_add_u64 v[66:67], v[62:63], 0, v[66:67]
	s_waitcnt vmcnt(7)
	ds_write2_b32 v14, v30, v31 offset1:1
	ds_write2_b32 v14, v32, v33 offset0:2 offset1:3
	s_waitcnt vmcnt(6)
	ds_write2_b32 v15, v34, v35 offset1:1
	ds_write2_b32 v17, v36, v37 offset1:1
	s_waitcnt vmcnt(5)
	ds_write2_b32 v18, v38, v39 offset1:1
	ds_write2_b32 v19, v40, v41 offset1:1
	s_waitcnt vmcnt(4)
	ds_write2_b32 v20, v42, v43 offset1:1
	ds_write2_b32 v21, v44, v45 offset1:1
	s_waitcnt vmcnt(3)
	ds_write2_b32 v22, v46, v47 offset1:1
	ds_write2_b32 v23, v48, v49 offset1:1
	s_waitcnt vmcnt(2)
	ds_write2_b32 v24, v50, v51 offset1:1
	ds_write2_b32 v25, v52, v53 offset1:1
	s_waitcnt vmcnt(1)
	ds_write2_b32 v26, v54, v55 offset1:1
	ds_write2_b32 v27, v56, v57 offset1:1
	s_waitcnt vmcnt(0)
	ds_write2_b32 v28, v58, v59 offset1:1
	ds_write2_b32 v29, v60, v61 offset1:1
	s_waitcnt lgkmcnt(0)
	ds_read2_b32 v[32:33], v13 offset0:33 offset1:41
	ds_read2_b32 v[34:35], v13 offset1:8
	ds_read2_b32 v[36:37], v13 offset0:66 offset1:74
	ds_read2_b32 v[38:39], v13 offset0:99 offset1:107
	ds_read2_b32 v[40:41], v13 offset0:132 offset1:140
	ds_read2_b32 v[42:43], v13 offset0:165 offset1:173
	ds_read2_b32 v[44:45], v13 offset0:198 offset1:206
	ds_read2_b32 v[46:47], v13 offset0:231 offset1:239
	ds_read2_b32 v[48:49], v13 offset0:49 offset1:57
	ds_read2_b32 v[50:51], v13 offset0:16 offset1:24
	ds_read2_b32 v[52:53], v13 offset0:82 offset1:90
	ds_read2_b32 v[54:55], v13 offset0:115 offset1:123
	ds_read2_b32 v[56:57], v13 offset0:148 offset1:156
	ds_read2_b32 v[58:59], v13 offset0:181 offset1:189
	ds_read2_b32 v[60:61], v13 offset0:214 offset1:222
	ds_read2_b32 v[70:71], v13 offset0:247 offset1:255
	s_waitcnt lgkmcnt(14)
	v_cvt_pk_bf16_f32 v30, v34, v32
	s_waitcnt lgkmcnt(12)
	v_cvt_pk_bf16_f32 v31, v36, v38
	v_cvt_pk_bf16_f32 v34, v35, v33
	s_waitcnt lgkmcnt(10)
	v_cvt_pk_bf16_f32 v32, v40, v42
	s_waitcnt lgkmcnt(8)
	v_cvt_pk_bf16_f32 v33, v44, v46
	v_cvt_pk_bf16_f32 v35, v37, v39
	v_cvt_pk_bf16_f32 v36, v41, v43
	v_cvt_pk_bf16_f32 v37, v45, v47
	global_store_dwordx4 v[68:69], v[30:33], off
	global_store_dwordx4 v[66:67], v[34:37], off
	s_waitcnt lgkmcnt(6)
	v_cvt_pk_bf16_f32 v38, v50, v48
	v_add_u32_e32 v30, 16, v64
	v_ashrrev_i32_e32 v31, 31, v30
	v_add_u32_e32 v34, 24, v64
	v_lshlrev_b64 v[30:31], 12, v[30:31]
	v_ashrrev_i32_e32 v35, 31, v34
	s_waitcnt lgkmcnt(4)
	v_cvt_pk_bf16_f32 v39, v52, v54
	s_waitcnt lgkmcnt(2)
	v_cvt_pk_bf16_f32 v40, v56, v58
	s_waitcnt lgkmcnt(0)
	v_cvt_pk_bf16_f32 v41, v60, v70
	v_lshl_add_u64 v[30:31], v[62:63], 0, v[30:31]
	v_lshlrev_b64 v[34:35], 12, v[34:35]
	global_store_dwordx4 v[30:31], v[38:41], off
	v_cvt_pk_bf16_f32 v30, v51, v49
	v_cvt_pk_bf16_f32 v31, v53, v55
	v_cvt_pk_bf16_f32 v32, v57, v59
	v_cvt_pk_bf16_f32 v33, v61, v71
	v_lshl_add_u64 v[34:35], v[62:63], 0, v[34:35]
	global_store_dwordx4 v[34:35], v[30:33], off
	s_waitcnt lgkmcnt(0)
	s_branch .LBB0_11

;     __device__ bool next(int i, Unit& u) const {
;         const long L = (long)i * G + c; if (c < 0 || L >= nwg) return false;
;         int wgid = (int)L; { const int q = nwg / NXCD, r = nwg % NXCD, xcd = wgid % NXCD, off = wgid / NXCD; wgid = (xcd < r ? xcd * (q + 1) : r * (q + 1) + (xcd - r) * q) + off; }
;         const int nig = WGM * nN, gid = wgid / nig, fm = gid * WGM, gsz = (nM - fm) < WGM ? (nM - fm) : WGM;
;         u.pm = fm + ((wgid % nig) % gsz); u.pn = (wgid % nig) / gsz; return true;
;     }
; template <class Epi, bool ALIGN_EPI>
; __device__ __forceinline__ void gemm_phase(LAS unsigned char* lds, const Gemm g, const StaticOrder& S, const Epi& E, const int wid) {
;     ...
;         const bool has_next = S.next(ui + 1, nxt);
;         const char* nA = has_next ? (const char*)g.A + (size_t)nxt.pm * tstep : cA; const char* nB = has_next ? (const char*)g.Bt + (size_t)nxt.pn * tstep : cB;
.LBB0_102:
	s_add_i32 s59, s59, 1
	s_cmp_lg_u32 s59, 2
	s_cbranch_scc1 .Ldw_ok
.Ldw_poll:
	v_mov_b32_e32 v252, 0
	global_load_dword v252, v252, s[88:89] offset:256 sc1
	s_waitcnt vmcnt(0)
	v_readfirstlane_b32 s4, v252
	s_cmp_ge_u32 s4, 32
	s_cbranch_scc1 .Ldw_ok
	s_sleep 2
	s_branch .Ldw_poll
.Ldw_ok:
	s_mul_i32 s4, s59, s62
	s_mul_hi_u32 s5, s59, s35
	s_add_i32 s5, s5, s4
	s_mul_i32 s4, s59, s35
	s_add_u32 s40, s4, s54
	s_addc_u32 s41, s5, 0
	v_cmp_gt_i64_e32 vcc, s[40:41], v[156:157]
	v_cmp_lt_i64_e64 s[4:5], s[40:41], v[154:155]
	s_cbranch_vccnz .LBB0_104
	s_ashr_i32 s36, s40, 31
	s_lshr_b32 s36, s36, 29
	s_add_i32 s36, s40, s36
	s_ashr_i32 s37, s36, 3
	s_and_b32 s36, s36, -8
	s_sub_i32 s36, s40, s36
	s_cmp_lt_i32 s36, 0
	s_cselect_b32 s38, s65, 0x70
	s_mul_i32 s36, s36, s38
	s_add_i32 s36, s36, s37
	s_mul_hi_i32 s37, s36, 0x92492493
	s_add_i32 s37, s37, s36
	s_lshr_b32 s38, s37, 31
	s_ashr_i32 s37, s37, 7
	s_add_i32 s37, s37, s38
	s_lshl_b32 s38, s37, 3
	s_sub_i32 s39, 32, s38
	s_min_i32 s39, s39, 8
	s_abs_i32 s40, s39
	v_cvt_f32_u32_e32 v0, s40
	s_sub_i32 s42, 0, s40
	s_mulk_i32 s37, 0xe0
	s_sub_i32 s37, s36, s37
	v_rcp_iflag_f32_e32 v0, v0
	s_abs_i32 s36, s37
	s_xor_b32 s41, s37, s39
	s_ashr_i32 s41, s41, 31
	v_mul_f32_e32 v0, 0x4f7ffffe, v0
	v_cvt_u32_f32_e32 v0, v0
	s_nop 0
	v_readfirstlane_b32 s43, v0
	s_mul_i32 s42, s42, s43
	s_mul_hi_u32 s42, s43, s42
	s_add_i32 s43, s43, s42
	s_mul_hi_u32 s42, s36, s43
	s_mul_i32 s43, s42, s40
	s_sub_i32 s36, s36, s43
	s_add_i32 s48, s42, 1
	s_sub_i32 s43, s36, s40
	s_cmp_ge_u32 s36, s40
	s_cselect_b32 s42, s48, s42
	s_cselect_b32 s36, s43, s36
	s_add_i32 s43, s42, 1
	s_cmp_ge_u32 s36, s40
	s_cselect_b32 s36, s43, s42
	s_xor_b32 s36, s36, s41
	s_sub_i32 s36, s36, s41
	s_mul_i32 s39, s36, s39
	s_sub_i32 s37, s37, s39
	s_add_i32 s38, s38, s37

; #define LAS __attribute__((address_space(3)))
; __device__ __forceinline__ unsigned cvtpk(float lo, float hi) { f32x2 v = {lo, hi}; bf16x2_t b = __builtin_convertvector(v, bf16x2_t); return __builtin_bit_cast(unsigned, b); }
; __device__ __forceinline__ void p0_transpose_item(const float* W, int K, int N, bf16_t* WT, const float* kscale, LAS float* scr, int item, int lane) {
;     const int nblk = N / 32, kb = item / nblk, nb = item % nblk, k0 = 64 * kb, n0 = 32 * nb;
;     const int n4 = (lane & 7) * 4, kr = lane >> 3;
;     f32x4 v[8];
; #pragma unroll
;     for (int i = 0; i < 8; ++i) v[i] = __builtin_nontemporal_load((const f32x4*)(W + (size_t)(k0 + kr + 8 * i) * N + n0 + n4));
; #pragma unroll
;     for (int i = 0; i < 8; ++i) { const int kk = kr + 8 * i; const float sc = kscale ? kscale[k0 + kk] : 1.0f; LAS float* d = scr + kk * 33 + n4;
;         d[0] = v[i].x * sc; d[1] = v[i].y * sc; d[2] = v[i].z * sc; d[3] = v[i].w * sc; }
;     asm volatile("s_waitcnt lgkmcnt(0)" ::: "memory");
;     const int c = lane & 7;
; #pragma unroll
;     for (int j = 0; j < 4; ++j) { const int n = (lane >> 3) + 8 * j; const LAS float* sp = scr + (8 * c) * 33 + n;
;         u32x4 o; o.x = cvtpk(sp[0 * 33], sp[1 * 33]); o.y = cvtpk(sp[2 * 33], sp[3 * 33]); o.z = cvtpk(sp[4 * 33], sp[5 * 33]); o.w = cvtpk(sp[6 * 33], sp[7 * 33]);
;         *(u32x4*)(WT + (size_t)(n0 + n) * K + k0 + 8 * c) = o; }
;     asm volatile("s_waitcnt lgkmcnt(0)" ::: "memory");
; }
; __global__ void __launch_bounds__(NWAVES * 64, 2) fwd(Args args) {
;     ...
;             const int first = split ? 224 : 0, nw = (G - first) * NWAVES;
;             if (bx >= first)
;                 for (int it = (bx - first) * NWAVES + wid; it < 2 * I_OUT; it += nw) {
;                     if (it < I_OUT) p0_transpose_item(w_out, DM, DM, WoutT, nullptr, scr, it, l3);
;                     else p0_transpose_item(w_gate, DM, DM, WgT, ple_norm, scr, it - I_OUT, l3);
;                 }
.LBB0_476:
	s_cmp_lt_u32 s77, 0xe0
	s_cbranch_scc1 .Ldw_skip
	s_load_dwordx2 s[50:51], s[80:81], 0x20018
	s_add_u32 s52, s80, 0x200000
	s_addc_u32 s53, s81, 0
	v_and_b32_e32 v16, 63, v185
	v_and_b32_e32 v2, 7, v16
	v_ashrrev_i32_e32 v9, 3, v16
	v_lshlrev_b32_e32 v6, 4, v2
	s_movk_i32 s48, 0x84
	v_add_u32_e32 v14, s61, v6
	v_mul_lo_u32 v15, v9, s48
	v_mov_b32_e32 v7, 0
	v_mul_u32_u24_e32 v4, 0x420, v2
	v_lshlrev_b32_e32 v5, 2, v9
	v_add_u32_e32 v14, v14, v15
	v_add3_u32 v13, s61, v4, v5
	s_waitcnt lgkmcnt(0)
	v_lshl_add_u64 v[4:5], s[50:51], 0, v[6:7]
	v_lshl_add_u64 v[6:7], s[52:53], 0, v[6:7]
	v_add_u32_e32 v15, 0x420, v14
	v_add_u32_e32 v17, 0x428, v14
	v_add_u32_e32 v18, 0x840, v14
	v_add_u32_e32 v19, 0x848, v14
	v_add_u32_e32 v20, 0xc60, v14
	v_add_u32_e32 v21, 0xc68, v14
	v_add_u32_e32 v22, 0x1080, v14
	v_add_u32_e32 v23, 0x1088, v14
	v_add_u32_e32 v24, 0x14a0, v14
	v_add_u32_e32 v25, 0x14a8, v14
	v_add_u32_e32 v26, 0x18c0, v14
	v_add_u32_e32 v27, 0x18c8, v14
	v_add_u32_e32 v28, 0x1ce0, v14
	v_add_u32_e32 v29, 0x1ce8, v14
	s_movk_i32 s42, 0x7000
	s_sub_i32 s43, s77, 0xe0
	s_lshl_b32 s43, s43, 3
	s_add_i32 s43, s43, s60
.Ldw_loop:
	s_cmpk_gt_i32 s43, 0xdff
	s_cbranch_scc1 .Ldw_done
	s_mul_i32 s41, s43, 0x925
	s_lshr_b32 s41, s41, 18
	s_mul_i32 s44, s41, 0x70
	s_sub_i32 s44, s43, s44
	s_cmp_ge_u32 s44, 56
	s_cselect_b32 s49, 0x70, 56
	s_add_i32 s44, s44, s49
	s_lshl_b32 s44, s44, 5
	s_lshl_b32 s40, s41, 6
	s_ashr_i32 s45, s44, 31
	v_add_u32_e32 v60, s40, v9
	v_lshl_add_u64 v[58:59], s[44:45], 2, v[4:5]
	v_mad_i64_i32 v[38:39], s[46:47], v60, s42, v[58:59]
	v_add_u32_e32 v30, 8, v60
	v_mad_i64_i32 v[40:41], s[46:47], v30, s42, v[58:59]
	global_load_dwordx4 v[30:33], v[38:39], off nt
	global_load_dwordx4 v[34:37], v[40:41], off nt
	v_add_u32_e32 v38, 16, v60
	v_mad_i64_i32 v[46:47], s[46:47], v38, s42, v[58:59]
	v_add_u32_e32 v38, 24, v60
	v_mad_i64_i32 v[48:49], s[46:47], v38, s42, v[58:59]
	global_load_dwordx4 v[38:41], v[46:47], off nt
	global_load_dwordx4 v[42:45], v[48:49], off nt
	v_add_u32_e32 v46, 32, v60
	v_mad_i64_i32 v[54:55], s[46:47], v46, s42, v[58:59]
	v_add_u32_e32 v46, 40, v60
	v_mad_i64_i32 v[56:57], s[46:47], v46, s42, v[58:59]
	global_load_dwordx4 v[46:49], v[54:55], off nt
	global_load_dwordx4 v[50:53], v[56:57], off nt
	v_add_u32_e32 v54, 48, v60
	v_mad_i64_i32 v[54:55], s[46:47], v54, s42, v[58:59]
	global_load_dwordx4 v[54:57], v[54:55], off nt
	v_add_u32_e32 v60, 56, v60
	v_mad_i64_i32 v[58:59], s[46:47], v60, s42, v[58:59]
	global_load_dwordx4 v[58:61], v[58:59], off nt
	v_add_u32_e32 v64, s44, v9
	s_ashr_i32 s41, s40, 31
	v_ashrrev_i32_e32 v65, 31, v64
	v_add_u32_e32 v66, 8, v64
	v_lshl_add_u64 v[62:63], s[40:41], 1, v[6:7]
	v_lshlrev_b64 v[68:69], 12, v[64:65]
	v_ashrrev_i32_e32 v67, 31, v66
	v_lshl_add_u64 v[68:69], v[62:63], 0, v[68:69]
	v_lshlrev_b64 v[66:67], 12, v[66:67]
	v_lshl_add_u64 v[66:67], v[62:63], 0, v[66:67]
	s_waitcnt vmcnt(7)
	ds_write2_b32 v14, v30, v31 offset1:1
	ds_write2_b32 v14, v32, v33 offset0:2 offset1:3
	s_waitcnt vmcnt(6)
	ds_write2_b32 v15, v34, v35 offset1:1
	ds_write2_b32 v17, v36, v37 offset1:1
	s_waitcnt vmcnt(5)
	ds_write2_b32 v18, v38, v39 offset1:1
	ds_write2_b32 v19, v40, v41 offset1:1
	s_waitcnt vmcnt(4)
	ds_write2_b32 v20, v42, v43 offset1:1
	ds_write2_b32 v21, v44, v45 offset1:1
	s_waitcnt vmcnt(3)
	ds_write2_b32 v22, v46, v47 offset1:1
	ds_write2_b32 v23, v48, v49 offset1:1
	s_waitcnt vmcnt(2)
	ds_write2_b32 v24, v50, v51 offset1:1
	ds_write2_b32 v25, v52, v53 offset1:1
	s_waitcnt vmcnt(1)
	ds_write2_b32 v26, v54, v55 offset1:1
	ds_write2_b32 v27, v56, v57 offset1:1
	s_waitcnt vmcnt(0)
	ds_write2_b32 v28, v58, v59 offset1:1
	ds_write2_b32 v29, v60, v61 offset1:1
	s_waitcnt lgkmcnt(0)
	ds_read2_b32 v[32:33], v13 offset0:33 offset1:41
	ds_read2_b32 v[34:35], v13 offset1:8
	ds_read2_b32 v[36:37], v13 offset0:66 offset1:74
	ds_read2_b32 v[38:39], v13 offset0:99 offset1:107
	ds_read2_b32 v[40:41], v13 offset0:132 offset1:140
	ds_read2_b32 v[42:43], v13 offset0:165 offset1:173
	ds_read2_b32 v[44:45], v13 offset0:198 offset1:206
	ds_read2_b32 v[46:47], v13 offset0:231 offset1:239
	ds_read2_b32 v[48:49], v13 offset0:49 offset1:57
	ds_read2_b32 v[50:51], v13 offset0:16 offset1:24
	ds_read2_b32 v[52:53], v13 offset0:82 offset1:90
	ds_read2_b32 v[54:55], v13 offset0:115 offset1:123
	ds_read2_b32 v[56:57], v13 offset0:148 offset1:156
	ds_read2_b32 v[58:59], v13 offset0:181 offset1:189
	ds_read2_b32 v[60:61], v13 offset0:214 offset1:222
	ds_read2_b32 v[70:71], v13 offset0:247 offset1:255
	s_waitcnt lgkmcnt(14)
	v_cvt_pk_bf16_f32 v30, v34, v32
	s_waitcnt lgkmcnt(12)
	v_cvt_pk_bf16_f32 v31, v36, v38
	v_cvt_pk_bf16_f32 v34, v35, v33
	s_waitcnt lgkmcnt(10)
	v_cvt_pk_bf16_f32 v32, v40, v42
	s_waitcnt lgkmcnt(8)
	v_cvt_pk_bf16_f32 v33, v44, v46
	v_cvt_pk_bf16_f32 v35, v37, v39
	v_cvt_pk_bf16_f32 v36, v41, v43
	v_cvt_pk_bf16_f32 v37, v45, v47
	global_store_dwordx4 v[68:69], v[30:33], off
	global_store_dwordx4 v[66:67], v[34:37], off
	s_waitcnt lgkmcnt(6)
	v_cvt_pk_bf16_f32 v38, v50, v48
	v_add_u32_e32 v30, 16, v64
	v_ashrrev_i32_e32 v31, 31, v30
	v_add_u32_e32 v34, 24, v64
	v_lshlrev_b64 v[30:31], 12, v[30:31]
	v_ashrrev_i32_e32 v35, 31, v34
	s_waitcnt lgkmcnt(4)
	v_cvt_pk_bf16_f32 v39, v52, v54
	s_waitcnt lgkmcnt(2)
	v_cvt_pk_bf16_f32 v40, v56, v58
	s_waitcnt lgkmcnt(0)
	v_cvt_pk_bf16_f32 v41, v60, v70
	v_lshl_add_u64 v[30:31], v[62:63], 0, v[30:31]
	v_lshlrev_b64 v[34:35], 12, v[34:35]
	global_store_dwordx4 v[30:31], v[38:41], off
	v_cvt_pk_bf16_f32 v30, v51, v49
	v_cvt_pk_bf16_f32 v31, v53, v55
	v_cvt_pk_bf16_f32 v32, v57, v59
	v_cvt_pk_bf16_f32 v33, v61, v71
	v_lshl_add_u64 v[34:35], v[62:63], 0, v[34:35]
	global_store_dwordx4 v[34:35], v[30:33], off
	s_waitcnt lgkmcnt(0)
	s_add_i32 s43, s43, 0x100
	s_branch .Ldw_loop
.Ldw_done:
	s_waitcnt vmcnt(0)
	s_barrier
	s_cmp_lg_u32 s60, 0
	s_cbranch_scc1 .Ldw_skip
	buffer_wbl2 sc1
	s_waitcnt vmcnt(0)
	v_mov_b32_e32 v0, 0
	v_mov_b32_e32 v1, 1
	s_mov_b64 s[46:47], exec
	s_mov_b64 exec, 1
	global_atomic_add v0, v1, s[88:89] offset:256
	s_mov_b64 exec, s[46:47]
